# P2 queue: up-projection tiles spread between the top-k jobs (blocks of 9 + 2) instead of after them
# baseline (speedup 1.0000x reference)
; __global__ void __launch_bounds__(NTHREADS) mega(Params p) {
;     ...
;       constexpr int NTK = 2 * 2052, NUP = 66 * 14, NJ = NTK + NUP + 16;
;       int pending = 0, par = 0;
;       if (threadIdx.x == 0) pending = (int)atomicAdd(p.ctr + l * 2 + 8 * rep, 1u);
;       for (;;) {
;         const int j = next_job(p.ctr + l * 2 + 8 * rep, lds, pending, NJ, par);
;         if (j >= NJ) break;
;         if (j < 16) {
;           cumsum_job(p, j, lds);
;         } else if (j < 16 + NTK) {
;           const int jj = j - 16;
;           const int b = jj & 1, q = 2051 - (jj >> 1);
;           topk_job(p, b, LEAD + 4 * q, lds);
;         } else {
;           const int u = j - 16 - NTK;
;           upproj_tile(p, u / 14, u % 14, lds);
;         }
.LBB0_618:
	s_sub_i32 s2, s87, 16
	s_cmpk_lt_u32 s2, 0x1398
	s_cbranch_scc0 .Ltks_a
	s_mul_i32 s3, s2, 0x1746
	s_lshr_b32 s3, s3, 16
	s_mul_i32 s87, s3, 11
	s_sub_i32 s2, s2, s87
	s_cmp_lt_u32 s2, 9
	s_cbranch_scc1 .Ltkm_a
	s_lshl_b32 s3, s3, 1
	s_add_i32 s3, s3, s2
	s_add_i32 s87, s3, 0x100f
	s_branch .Ltks_a
.Ltkm_a:
	s_mul_i32 s3, s3, 9
	s_add_i32 s2, s3, s2
	s_cmpk_lt_u32 s2, 0x804
	s_cselect_b32 s3, 0, 1
	s_cbranch_scc1 .Ltkb_a
	s_sub_i32 s2, s2, 0x804

; DI int next_job(unsigned* ctr, char* lds, int& pending, int njobs, int& par) {
;   int* sj = (int*)(lds + LDS_JOB);
;   if (threadIdx.x == 0) sj[par] = pending;
;   __syncthreads();
;   const int j = sj[par];
;   par ^= 1;
;   if (threadIdx.x == 0 && j < njobs) pending = (int)atomicAdd(ctr, 1u);
;   return j;
; __global__ void __launch_bounds__(NTHREADS) mega(Params p) {
;     ...
;         const int j = next_job(p.ctr + l * 2 + 8 * rep, lds, pending, NJ, par);
;         if (j >= NJ) break;
;         if (j < 16) {
;           cumsum_job(p, j, lds);
;         } else if (j < 16 + NTK) {
;           const int jj = j - 16;
;           const int b = jj & 1, q = 2051 - (jj >> 1);
;           topk_job(p, b, LEAD + 4 * q, lds);
;         } else {
;           const int u = j - 16 - NTK;
;           upproj_tile(p, u / 14, u % 14, lds);
;         }
.Lsc_end:
	s_waitcnt vmcnt(0) lgkmcnt(0)
	v_lshrrev_b32_e32 v0, 6, v100
	s_mov_b32 s3, s90
	v_readfirstlane_b32 s2, v0
	s_lshl_b32 s4, s87, 1
	s_and_b32 s4, s4, 0x3ffc
	s_sub_i32 s4, 0x209c, s4
	s_bitcmp1_b32 s87, 0
	s_cselect_b32 s5, 0x2100, 0
	s_add_i32 s4, s4, s5
	v_readlane_b32 s6, v240, 13
	v_readlane_b32 s7, v240, 14
	s_lshl_b32 s5, s4, 9
	s_add_u32 s40, s6, s5
	s_addc_u32 s41, s7, 0
	s_add_u32 s42, s40, 0x200
	s_addc_u32 s43, s41, 0
	s_add_u32 s44, s42, 0x200
	s_addc_u32 s45, s43, 0
	s_add_u32 s46, s44, 0x200
	s_addc_u32 s47, s45, 0
	s_mov_b32 s16, 0x55555555
	s_mov_b32 s17, 0x55555555
	s_mov_b32 s18, 0x33333333
	s_mov_b32 s19, 0x33333333
	s_mov_b32 s20, 0xf0f0f0f
	s_mov_b32 s21, 0xf0f0f0f
	s_mov_b32 s22, 0xff00ff
	s_mov_b32 s23, 0xff00ff
	s_mov_b32 s24, 0xffff
	s_mov_b32 s25, 0xffff
	s_mov_b32 s26, 0xffffffff
	s_mov_b32 s27, 0
	v_mov_b32_e32 v20, 1
	v_and_b32_e32 v0, 3, v101
	v_lshlrev_b32_e32 v0, 12, v0
	v_add_u32_e32 v21, 0x4000, v0
	v_add_u32_e32 v25, 0x14000, v0
	v_mov_b32_e32 v29, 0x4000
	v_add_u32_e32 v22, 0x8000, v0
	v_add_u32_e32 v26, 0x18000, v0
	v_mov_b32_e32 v30, 0x8000
	v_add_u32_e32 v23, 0xc000, v0
	v_add_u32_e32 v27, 0x1c000, v0
	v_mov_b32_e32 v31, 0xc000
	v_add_u32_e32 v24, 0x10000, v0
	v_add_u32_e32 v28, 0x20000, v0
	v_mov_b32_e32 v32, 0x10000
	s_movk_i32 s85, 0x100
	s_mov_b32 s56, 0
	s_mov_b32 s58, 0
	v_cmp_eq_u32_e32 vcc, 0, v100
	s_and_saveexec_b64 s[30:31], vcc
	ds_write_b32 v3, v136 offset:768
	s_mov_b64 exec, s[30:31]
	s_waitcnt lgkmcnt(0)
	v_lshlrev_b32_e32 v75, 2, v100
	v_add_u32_e32 v75, 0x2800, v75
	v_lshlrev_b32_e32 v76, 1, v100
	v_add_u32_e32 v76, 0x800, v76
	s_barrier
	v_mov_b32_e32 v4, 0
	v_mov_b32_e32 v5, 0
	v_mov_b32_e32 v6, 0
	v_mov_b32_e32 v7, 0
	v_lshlrev_b32_e32 v0, 4, v100
	v_add_u32_e32 v0, 0x4000, v0
	v_add_u32_e32 v1, 0x10000, v0
	ds_write_b128 v0, v[4:7]
	ds_write_b128 v0, v[4:7] offset:8192
	ds_write_b128 v0, v[4:7] offset:16384
	ds_write_b128 v0, v[4:7] offset:24576
	ds_write_b128 v0, v[4:7] offset:32768
	ds_write_b128 v0, v[4:7] offset:40960
	ds_write_b128 v0, v[4:7] offset:49152
	ds_write_b128 v0, v[4:7] offset:57344
	v_mov_b32_e32 v2, -1
	v_lshlrev_b32_e32 v0, 2, v100
	ds_write_b32 v0, v2 offset:8192
	s_waitcnt lgkmcnt(0)
	s_barrier
	ds_read_b32 v0, v3 offset:768
	s_waitcnt lgkmcnt(0)
	v_readfirstlane_b32 s63, v0
	s_sub_i32 s4, s63, 16
	s_cmpk_lt_u32 s4, 0x1398
	s_cbranch_scc0 .Ltks_b
	s_mul_i32 s5, s4, 0x1746
	s_lshr_b32 s5, s5, 16
	s_mul_i32 s63, s5, 11
	s_sub_i32 s4, s4, s63
	s_cmp_lt_u32 s4, 9
	s_cbranch_scc1 .Ltkm_b
	s_lshl_b32 s5, s5, 1
	s_add_i32 s5, s5, s4
	s_add_i32 s63, s5, 0x100f
	s_branch .Ltks_b
.Ltkm_b:
	s_mul_i32 s5, s5, 9
	s_add_i32 s4, s5, s4
	s_cmpk_lt_u32 s4, 0x804
	s_cselect_b32 s5, 0, 1
	s_cbranch_scc1 .Ltkb_b
	s_sub_i32 s4, s4, 0x804
